# combined: xattn QK ladders de-serialised + P5 back-edge rotation + xattn row-sum tree
# speedup vs baseline: 1.0039x; 1.0013x over previous
;     ...
;         for (int ks = 0; ks < DQK / 32; ++ks)
; #pragma unroll
;             for (int ni = 0; ni < 4; ++ni) { const bf16x8 kf = *(const bf16x8*)(cK + (ni * 16 + fr) * LDK + ks * 32 + fq * 8);
; #pragma unroll
;                 for (int mi = 0; mi < MIA; ++mi) s[mi][ni] = __builtin_amdgcn_mfma_f32_16x16x32_bf16(kf, qf[mi][ks], s[mi][ni], 0, 0, 0); }
;         }
;         __syncthreads();
;         slot = nslot;
;         if (live) {
;         bf16x8 pf[MIA][2];
; #pragma unroll
;         for (int mi = 0; mi < MIA; ++mi) {
;             float mx = -1e30f;
;             if (CAUSAL && kt * 64 + 63 > q0 + w * 16 * MIA) {
;                 const int qabs = q0 + w * 16 * MIA + mi * 16 + fr;
; #pragma unroll
;                 for (int ni = 0; ni < 4; ++ni)
; #pragma unroll
;                     for (int r = 0; r < 4; ++r) { const int kabs = kt * 64 + ni * 16 + fq * 4 + r; if (kabs > qabs) s[mi][ni][r] = -1e30f; }
;             }
; #pragma unroll
;             for (int ni = 0; ni < 4; ++ni) mx = fmaxf(mx, fmaxf(fmaxf(s[mi][ni][0], s[mi][ni][1]), fmaxf(s[mi][ni][2], s[mi][ni][3])));
;             mx = fmaxf(mx, __shfl_xor(mx, 16)); mx = fmaxf(mx, __shfl_xor(mx, 32));
;             const float mnew = fmaxf(mrun[mi], mx);
;             const float mc = mnew * scale_log2;
;             float ps = 0.f;
; #pragma unroll
;             for (int ni = 0; ni < 4; ++ni)
; #pragma unroll
;                 for (int r = 0; r < 4; ++r) { const float pv = __builtin_amdgcn_exp2f(__builtin_fmaf(s[mi][ni][r], scale_log2, -mc)); s[mi][ni][r] = pv; ps += pv; }
;             if (__builtin_amdgcn_ballot_w64(mnew > mrun[mi]) != 0ull) {
;                 const float alpha = __builtin_amdgcn_exp2f((mrun[mi] - mnew) * scale_log2);
;                 lrun[mi] *= alpha;
; #pragma unroll
;                 for (int di = 0; di < DV / 16; ++di) o[mi][di] *= alpha;
;             }
;             mrun[mi] = mnew;
;             lrun[mi] += ps;
.LBB0_387:
	s_or_b64 exec, exec, s[0:1]
	s_waitcnt vmcnt(2)
	v_pk_add_f32 v[102:103], v[102:103], v[104:105]
	v_pk_add_f32 v[106:107], v[106:107], v[108:109]
	v_pk_add_f32 v[72:73], v[72:73], v[74:75]
	v_pk_add_f32 v[76:77], v[76:77], v[78:79]
	v_pk_add_f32 v[102:103], v[102:103], v[106:107]
	v_pk_add_f32 v[72:73], v[72:73], v[76:77]
	v_pk_add_f32 v[102:103], v[102:103], v[72:73]
	v_add_f32_e32 v16, v102, v103
	s_waitcnt vmcnt(1)
	ds_write_b128 v95, v[24:27] offset:18432
	s_waitcnt vmcnt(0)
	ds_write_b128 v96, v[28:31] offset:18432
	v_add_u32_e32 v69, 0x12000, v90
	v_add_f32_e32 v68, v16, v99
	ds_read_b128 v[104:107], v69
	ds_read_b128 v[108:111], v69 offset:4608
	ds_read_b128 v[112:115], v69 offset:9216
	ds_read_b128 v[116:119], v69 offset:13824
	ds_read_b128 v[120:123], v69 offset:64
	ds_read_b128 v[124:127], v69 offset:4672
	ds_read_b128 v[128:131], v69 offset:9280
	ds_read_b128 v[132:135], v69 offset:13888
	s_waitcnt lgkmcnt(7)
	v_mfma_f32_16x16x32_bf16 v[20:23], v[104:107], v[12:15], 0
	ds_read_b128 v[136:139], v69 offset:128
	s_waitcnt lgkmcnt(7)
	v_mfma_f32_16x16x32_bf16 v[28:31], v[108:111], v[12:15], 0
	ds_read_b128 v[140:143], v69 offset:4736
	s_waitcnt lgkmcnt(7)
	v_mfma_f32_16x16x32_bf16 v[24:27], v[112:115], v[12:15], 0
	ds_read_b128 v[144:147], v69 offset:9344
	s_waitcnt lgkmcnt(7)
	v_mfma_f32_16x16x32_bf16 v[16:19], v[116:119], v[12:15], 0
	ds_read_b128 v[148:151], v69 offset:13952
	s_waitcnt lgkmcnt(7)
	v_mfma_f32_16x16x32_bf16 v[20:23], v[120:123], v[8:11], v[20:23]
	ds_read_b128 v[104:107], v69 offset:192
	s_waitcnt lgkmcnt(7)
	v_mfma_f32_16x16x32_bf16 v[28:31], v[124:127], v[8:11], v[28:31]
	ds_read_b128 v[108:111], v69 offset:4800
	s_waitcnt lgkmcnt(7)
	v_mfma_f32_16x16x32_bf16 v[24:27], v[128:131], v[8:11], v[24:27]
	ds_read_b128 v[112:115], v69 offset:9408
	s_waitcnt lgkmcnt(7)
	v_mfma_f32_16x16x32_bf16 v[16:19], v[132:135], v[8:11], v[16:19]
	ds_read_b128 v[116:119], v69 offset:14016
	s_waitcnt lgkmcnt(7)
	v_mfma_f32_16x16x32_bf16 v[20:23], v[136:139], v[4:7], v[20:23]
	s_waitcnt lgkmcnt(6)
	v_mfma_f32_16x16x32_bf16 v[28:31], v[140:143], v[4:7], v[28:31]
	s_waitcnt lgkmcnt(5)
	v_mfma_f32_16x16x32_bf16 v[24:27], v[144:147], v[4:7], v[24:27]
	s_waitcnt lgkmcnt(4)
	v_mfma_f32_16x16x32_bf16 v[16:19], v[148:151], v[4:7], v[16:19]
	s_waitcnt lgkmcnt(3)
	v_mfma_f32_16x16x32_bf16 v[20:23], v[104:107], v[0:3], v[20:23]
	s_waitcnt lgkmcnt(2)
	v_mfma_f32_16x16x32_bf16 v[28:31], v[108:111], v[0:3], v[28:31]
	s_waitcnt lgkmcnt(1)
	v_mfma_f32_16x16x32_bf16 v[24:27], v[112:115], v[0:3], v[24:27]
	s_waitcnt lgkmcnt(0)
	v_mfma_f32_16x16x32_bf16 v[16:19], v[116:119], v[0:3], v[16:19]
	v_max_f32_e32 v64, v23, v23
	v_max_f32_e32 v65, v22, v22
	v_max_f32_e32 v64, v65, v64
	v_max_f32_e32 v65, v31, v31
	v_max_f32_e32 v66, v30, v30
	v_max_f32_e32 v65, v66, v65
	v_max3_f32 v64, v20, v21, v64
	v_max3_f32 v65, v28, v29, v65
	v_max3_f32 v64, v64, s17, v65
	v_max_f32_e32 v65, v27, v27
	v_max_f32_e32 v66, v26, v26
	v_max_f32_e32 v65, v66, v65
	v_max_f32_e32 v66, v19, v19
	v_max_f32_e32 v67, v18, v18
	v_max_f32_e32 v66, v67, v66
	v_max3_f32 v65, v24, v25, v65
	v_max3_f32 v66, v16, v17, v66
	v_max3_f32 v64, v64, v65, v66
	ds_bpermute_b32 v65, v82, v64
	s_waitcnt lgkmcnt(0)
	s_barrier
	v_max_f32_e32 v65, v65, v65
	v_max_f32_e32 v64, v64, v65
	ds_bpermute_b32 v65, v83, v64
	s_waitcnt lgkmcnt(0)
	v_max3_f32 v69, v101, v64, v65
	v_cmp_gt_f32_e32 vcc, v69, v101
	s_cbranch_vccz .LBB0_389
	v_sub_f32_e32 v64, v101, v69
	v_mul_f32_e32 v64, 0x3e0293ee, v64
	v_exp_f32_e32 v64, v64
	s_nop 0
	v_pk_mul_f32 v[38:39], v[38:39], v[64:65] op_sel_hi:[1,0]
	v_pk_mul_f32 v[36:37], v[36:37], v[64:65] op_sel_hi:[1,0]
	v_pk_mul_f32 v[50:51], v[50:51], v[64:65] op_sel_hi:[1,0]
	v_pk_mul_f32 v[48:49], v[48:49], v[64:65] op_sel_hi:[1,0]
	v_pk_mul_f32 v[54:55], v[54:55], v[64:65] op_sel_hi:[1,0]
	v_pk_mul_f32 v[52:53], v[52:53], v[64:65] op_sel_hi:[1,0]
	v_pk_mul_f32 v[58:59], v[58:59], v[64:65] op_sel_hi:[1,0]
	v_pk_mul_f32 v[56:57], v[56:57], v[64:65] op_sel_hi:[1,0]
	v_pk_mul_f32 v[62:63], v[62:63], v[64:65] op_sel_hi:[1,0]
	v_pk_mul_f32 v[60:61], v[60:61], v[64:65] op_sel_hi:[1,0]
	v_pk_mul_f32 v[46:47], v[46:47], v[64:65] op_sel_hi:[1,0]
	v_pk_mul_f32 v[44:45], v[44:45], v[64:65] op_sel_hi:[1,0]
	v_pk_mul_f32 v[42:43], v[42:43], v[64:65] op_sel_hi:[1,0]
	v_pk_mul_f32 v[40:41], v[40:41], v[64:65] op_sel_hi:[1,0]
	v_pk_mul_f32 v[34:35], v[34:35], v[64:65] op_sel_hi:[1,0]
	v_pk_mul_f32 v[32:33], v[32:33], v[64:65] op_sel_hi:[1,0]
	v_mul_f32_e32 v68, v68, v64
